# w_in GEMM third round (88 tiles) also split into 128-column halves over two workgroups (half B loads, MFMAs, epilogue guards); on top of the ffn1 split
# speedup vs baseline: 1.0162x; 1.0103x over previous
.LBB0_503:
	s_lshl_b32 s7, s7, 5
	s_and_b32 s11, s7, 0x60
	s_add_i32 m0, s35, 0x18000
	v_lshl_add_u64 v[6:7], v[6:7], 0, s[2:3]
	s_lshl_b32 s77, s8, 6
	s_lshl_b32 s10, s8, 13
	s_lshl_b32 s7, s11, 7
	s_waitcnt vmcnt(2)
	s_barrier
	global_load_lds_dwordx4 v[6:7], off
	v_lshl_add_u64 v[4:5], v[4:5], 0, s[2:3]
	s_add_i32 m0, s35, 0x1a000
	s_add_i32 s78, s35, 0x8000
	s_add_i32 s79, s35, 0xa000
	global_load_lds_dwordx4 v[4:5], off
	v_lshl_add_u64 v[0:1], v[0:1], 0, s[2:3]
	s_mov_b32 m0, s78
	s_add_u32 s8, s22, 0x40080
	global_load_lds_dwordx4 v[0:1], off
	v_lshl_add_u64 v[0:1], v[2:3], 0, s[2:3]
	s_mov_b32 m0, s79
	s_addc_u32 s9, s23, 0
	global_load_lds_dwordx4 v[0:1], off
	s_add_i32 m0, s35, 0x1c000
	v_lshl_add_u64 v[0:1], s[8:9], 0, v[142:143]
	global_load_lds_dwordx4 v[0:1], off
	v_lshl_add_u64 v[0:1], s[8:9], 0, v[138:139]
	s_add_i32 m0, s35, 0x1e000
	v_and_b32_e32 v156, 15, v10
	global_load_lds_dwordx4 v[0:1], off
	v_lshrrev_b32_e32 v0, 1, v10
	v_and_b32_e32 v0, 24, v0
	v_lshlrev_b32_e32 v1, 1, v0
	v_lshlrev_b32_e32 v2, 2, v10
	v_or_b32_e32 v158, s11, v0
	v_lshlrev_b32_e32 v0, 14, v13
	v_lshl_or_b32 v1, v156, 6, v1
	v_and_b32_e32 v2, 32, v2
	s_cmpk_lt_u32 s6, 0x100
	v_and_b32_e32 v0, 0xffff8000, v0
	v_bitop3_b32 v3, v1, s10, v2 bitop3:0xde
	v_bitop3_b32 v157, v1, s7, v2 bitop3:0xde
	s_cselect_b64 s[6:7], -1, 0
	s_waitcnt lgkmcnt(0)
	s_ashr_i32 s80, s76, 31
	v_lshl_add_u32 v0, v12, 11, v0
	v_and_b32_e32 v1, 1, v13
	s_add_u32 s8, s84, 0x664a000
	v_lshl_or_b32 v0, v1, 6, v0
	s_addc_u32 s9, s85, 0
	v_readlane_b32 s12, v254, 38
	v_lshl_add_u32 v146, v14, 1, v0
	v_lshlrev_b32_e32 v0, 14, v8
	v_readlane_b32 s13, v254, 39
	s_add_u32 s10, s12, 0x6800000
	v_and_b32_e32 v0, 0xffff8000, v0
	s_waitcnt vmcnt(6)
	s_addc_u32 s11, s13, 0
	v_lshl_add_u32 v0, v9, 11, v0
	v_and_b32_e32 v1, 1, v8
	s_add_u32 s12, s12, 0x2800000
	v_lshl_or_b32 v0, v1, 6, v0
	v_readlane_b32 s14, v253, 8
	v_or_b32_e32 v159, 16, v156
	v_or_b32_e32 v176, 32, v156
	v_or_b32_e32 v177, 48, v156
	s_addc_u32 s13, s13, 0
	v_mov_b32_e32 v147, v129
	v_lshl_add_u32 v148, v11, 1, v0
	v_mov_b32_e32 v149, v129
	s_mov_b32 s81, 0
	v_add_u32_e32 v178, 0, v3
	v_readlane_b32 s26, v252, 37
	s_mov_b32 s27, s14
	s_barrier
	v_readlane_b32 s15, v253, 9
	s_mov_b32 s70, 0
	s_mov_b32 s72, 0
	s_branch .LBB0_506

.LBB0_505:
	s_mov_b32 s72, s70
	s_andn2_b64 vcc, exec, s[0:1]
	s_mov_b32 s26, s14
	s_mov_b32 s27, s16
	s_mov_b64 s[22:23], s[20:21]
	s_mov_b64 s[0:1], s[18:19]
	s_cbranch_vccz .LBB0_675
.LBB0_506:
	s_add_i32 s81, s81, 1
	s_mul_i32 s15, s81, s80
	s_mul_hi_u32 s17, s81, s76
	s_add_i32 s17, s17, s15
	s_mul_i32 s15, s81, s76
	v_readlane_b32 s18, v252, 0
	s_add_u32 s18, s15, s18
	v_readlane_b32 s15, v252, 10
	s_addc_u32 s19, s17, s15
	s_cmp_eq_u32 s81, 2
	s_cbranch_scc0 .Lq_full_W
	v_readlane_b32 s15, v252, 0
	s_and_b32 s70, s15, 1
	s_add_i32 s70, s70, 1
	s_lshr_b32 s18, s15, 1
	s_addk_i32 s18, 0x200
	s_mov_b32 s19, 0
	s_branch .Lq_cont_W

.Lq_cont_W:
	v_mov_b64_e32 v[0:1], 0x258
	v_cmp_lt_i64_e64 s[36:37], s[18:19], v[0:1]
	v_mov_b64_e32 v[0:1], 0x257
	v_cmp_gt_i64_e32 vcc, s[18:19], v[0:1]
	s_cbranch_vccnz .LBB0_508
	s_ashr_i32 s14, s18, 31
	s_lshr_b32 s14, s14, 29
	s_add_i32 s14, s18, s14
	s_ashr_i32 s15, s14, 3
	s_and_b32 s14, s14, -8
	s_sub_i32 s14, s18, s14
	s_cmp_lt_i32 s14, 0
	s_movk_i32 s16, 0x4c
	s_cselect_b32 s16, s16, 0x4b
	s_mul_i32 s14, s16, s14
	s_add_i32 s14, s14, s15
	s_mul_hi_i32 s15, s14, 0x88888889
	s_add_i32 s15, s15, s14
	s_lshr_b32 s16, s15, 31
	s_ashr_i32 s15, s15, 6
	s_add_i32 s15, s15, s16
	s_lshl_b32 s16, s15, 3
	s_sub_i32 s17, 40, s16
	s_min_i32 s17, s17, 8
	s_abs_i32 s18, s17
	v_cvt_f32_u32_e32 v0, s18
	s_sub_i32 s20, 0, s18
	s_mulk_i32 s15, 0x78
	s_sub_i32 s15, s14, s15
	v_rcp_iflag_f32_e32 v0, v0
	s_abs_i32 s14, s15
	s_xor_b32 s19, s15, s17
	s_ashr_i32 s19, s19, 31
	v_mul_f32_e32 v0, 0x4f7ffffe, v0
	v_cvt_u32_f32_e32 v0, v0
	s_nop 0
	v_readfirstlane_b32 s21, v0
	s_mul_i32 s20, s20, s21
	s_mul_hi_u32 s20, s21, s20
	s_add_i32 s21, s21, s20
	s_mul_hi_u32 s20, s14, s21
	s_mul_i32 s21, s20, s18
	s_sub_i32 s14, s14, s21
	s_add_i32 s24, s20, 1
	s_sub_i32 s21, s14, s18
	s_cmp_ge_u32 s14, s18
	s_cselect_b32 s20, s24, s20
	s_cselect_b32 s14, s21, s14
	s_add_i32 s21, s20, 1
	s_cmp_ge_u32 s14, s18
	s_cselect_b32 s14, s21, s20
	s_xor_b32 s14, s14, s19
	s_sub_i32 s14, s14, s19
	s_mul_i32 s17, s14, s17
	s_sub_i32 s15, s15, s17
	s_add_i32 s16, s15, s16
.LBB0_508:
	s_ashr_i32 s17, s16, 31
	s_lshl_b64 s[18:19], s[16:17], 19
	v_readlane_b32 s20, v254, 36
	v_readlane_b32 s21, v254, 37
	s_add_u32 s18, s20, s18
	s_addc_u32 s19, s21, s19
	s_and_b64 s[20:21], s[36:37], exec
	s_cselect_b32 s17, s19, s1
	s_cselect_b32 s28, s18, s0
	s_ashr_i32 s15, s14, 31
	s_lshl_b64 s[20:21], s[14:15], 19
	s_add_u32 s20, s30, s20
	s_addc_u32 s21, s31, s21
	s_and_b64 s[24:25], s[36:37], exec
	s_cselect_b32 s15, s21, s23
	s_cselect_b32 s29, s20, s22
	s_add_u32 s0, s0, 0x40080
	s_addc_u32 s1, s1, 0
	s_add_u32 s33, s22, 0x100
	v_mov_b32_e32 v0, 0
	s_addc_u32 s38, s23, 0
	s_mov_b32 s39, -2
	v_mov_b32_e32 v1, v0
	v_mov_b32_e32 v2, v0
	v_mov_b32_e32 v3, v0
	v_mov_b32_e32 v4, v0
	v_mov_b32_e32 v5, v0
	v_mov_b32_e32 v6, v0
	v_mov_b32_e32 v7, v0
	v_mov_b32_e32 v16, v0
	v_mov_b32_e32 v17, v0
	v_mov_b32_e32 v18, v0
	v_mov_b32_e32 v19, v0
	v_mov_b32_e32 v20, v0
	v_mov_b32_e32 v21, v0
	v_mov_b32_e32 v22, v0
	v_mov_b32_e32 v23, v0
	v_mov_b32_e32 v32, v0
	v_mov_b32_e32 v33, v0
	v_mov_b32_e32 v34, v0
	v_mov_b32_e32 v35, v0
	v_mov_b32_e32 v36, v0
	v_mov_b32_e32 v37, v0
	v_mov_b32_e32 v38, v0
	v_mov_b32_e32 v39, v0
	v_mov_b32_e32 v48, v0
	v_mov_b32_e32 v49, v0
	v_mov_b32_e32 v50, v0
	v_mov_b32_e32 v51, v0
	v_mov_b32_e32 v52, v0
	v_mov_b32_e32 v53, v0
	v_mov_b32_e32 v54, v0
	v_mov_b32_e32 v55, v0
	v_mov_b32_e32 v8, v0
	v_mov_b32_e32 v9, v0
	v_mov_b32_e32 v10, v0
	v_mov_b32_e32 v11, v0
	v_mov_b32_e32 v12, v0
	v_mov_b32_e32 v13, v0
	v_mov_b32_e32 v14, v0
	v_mov_b32_e32 v15, v0
	v_mov_b32_e32 v24, v0
	v_mov_b32_e32 v25, v0
	v_mov_b32_e32 v26, v0
	v_mov_b32_e32 v27, v0
	v_mov_b32_e32 v28, v0
	v_mov_b32_e32 v29, v0
	v_mov_b32_e32 v30, v0
	v_mov_b32_e32 v31, v0
	v_mov_b32_e32 v40, v0
	v_mov_b32_e32 v41, v0
	v_mov_b32_e32 v42, v0
	v_mov_b32_e32 v43, v0
	v_mov_b32_e32 v44, v0
	v_mov_b32_e32 v45, v0
	v_mov_b32_e32 v46, v0
	v_mov_b32_e32 v47, v0
	v_mov_b32_e32 v56, v0
	v_mov_b32_e32 v57, v0
	v_mov_b32_e32 v58, v0
	v_mov_b32_e32 v59, v0
	v_mov_b32_e32 v60, v0
	v_mov_b32_e32 v61, v0
	v_mov_b32_e32 v62, v0
	v_mov_b32_e32 v63, v0
	v_mov_b32_e32 v64, v0
	v_mov_b32_e32 v65, v0
	v_mov_b32_e32 v66, v0
	v_mov_b32_e32 v67, v0
	v_mov_b32_e32 v68, v0
	v_mov_b32_e32 v69, v0
	v_mov_b32_e32 v70, v0
	v_mov_b32_e32 v71, v0
	v_mov_b32_e32 v80, v0
	v_mov_b32_e32 v81, v0
	v_mov_b32_e32 v82, v0
	v_mov_b32_e32 v83, v0
	v_mov_b32_e32 v84, v0
	v_mov_b32_e32 v85, v0
	v_mov_b32_e32 v86, v0
	v_mov_b32_e32 v87, v0
	v_mov_b32_e32 v96, v0
	v_mov_b32_e32 v97, v0
	v_mov_b32_e32 v98, v0
	v_mov_b32_e32 v99, v0
	v_mov_b32_e32 v100, v0
	v_mov_b32_e32 v101, v0
	v_mov_b32_e32 v102, v0
	v_mov_b32_e32 v103, v0
	v_mov_b32_e32 v112, v0
	v_mov_b32_e32 v113, v0
	v_mov_b32_e32 v114, v0
	v_mov_b32_e32 v115, v0
	v_mov_b32_e32 v116, v0
	v_mov_b32_e32 v117, v0
	v_mov_b32_e32 v118, v0
	v_mov_b32_e32 v119, v0
	v_mov_b32_e32 v72, v0
	v_mov_b32_e32 v73, v0
	v_mov_b32_e32 v74, v0
	v_mov_b32_e32 v75, v0
	v_mov_b32_e32 v76, v0
	v_mov_b32_e32 v77, v0
	v_mov_b32_e32 v78, v0
	v_mov_b32_e32 v79, v0
	v_mov_b32_e32 v88, v0
	v_mov_b32_e32 v89, v0
	v_mov_b32_e32 v90, v0
	v_mov_b32_e32 v91, v0
	v_mov_b32_e32 v92, v0
	v_mov_b32_e32 v93, v0
	v_mov_b32_e32 v94, v0
	v_mov_b32_e32 v95, v0
	v_mov_b32_e32 v104, v0
	v_mov_b32_e32 v105, v0
	v_mov_b32_e32 v106, v0
	v_mov_b32_e32 v107, v0
	v_mov_b32_e32 v108, v0
	v_mov_b32_e32 v109, v0
	v_mov_b32_e32 v110, v0
	v_mov_b32_e32 v111, v0
	v_mov_b32_e32 v120, v0
	v_mov_b32_e32 v121, v0
	v_mov_b32_e32 v122, v0
	v_mov_b32_e32 v123, v0
	v_mov_b32_e32 v124, v0
	v_mov_b32_e32 v125, v0
	v_mov_b32_e32 v126, v0
	v_mov_b32_e32 v127, v0
	s_cmp_lg_u32 s72, 0
	s_cbranch_scc1 .Lhalf_sel_W

.Lhalf_sel_W:
	s_cmp_eq_u32 s72, 1
	s_cbranch_scc1 .Lh0_W_509
	s_branch .Lh1_W_509
.Lh0_W_509:
	s_add_u32 s22, s0, 0xfffc0080
	s_addc_u32 s23, s1, -1
	s_add_i32 s40, 0, 0x10000
	s_cmp_eq_u32 s39, 12
	s_cselect_b32 s25, s17, s23
	s_cselect_b32 s24, s28, s22
	v_add_u32_e32 v128, s40, v157
	s_cselect_b32 s23, s15, s38
	s_cselect_b32 s22, s29, s33
	s_add_i32 s44, 0, 0x14000
	ds_read_b128 v[150:153], v128
	ds_read_b128 v[190:193], v128 offset:1024
	ds_read_b128 v[194:197], v128 offset:2048
	ds_read_b128 v[198:201], v128 offset:3072
	v_add_u32_e32 v128, s44, v157
	v_lshl_add_u64 v[154:155], s[0:1], 0, v[146:147]
	s_add_i32 m0, s35, 0xc000
	ds_read_b128 v[218:221], v178
	ds_read_b128 v[222:225], v178 offset:1024
	ds_read_b128 v[226:229], v178 offset:2048
	ds_read_b128 v[230:233], v178 offset:3072
	ds_read_b128 v[234:237], v178 offset:4096
	ds_read_b128 v[238:241], v178 offset:5120
	ds_read_b128 v[242:245], v178 offset:6144
	ds_read_b128 v[246:249], v178 offset:7168
	global_load_lds_dwordx4 v[154:155], off
	v_lshl_add_u64 v[154:155], s[0:1], 0, v[148:149]
	s_add_i32 m0, s35, 0xe000
	s_nop 0
	global_load_lds_dwordx4 v[154:155], off
	s_waitcnt vmcnt(6)
	s_waitcnt lgkmcnt(0)
	s_barrier
	s_setprio 1
	s_waitcnt lgkmcnt(0)
	v_mfma_f32_16x16x32_bf16 v[124:127], v[150:153], v[218:221], v[124:127]
	v_mfma_f32_16x16x32_bf16 v[120:123], v[194:197], v[218:221], v[120:123]
	v_mfma_f32_16x16x32_bf16 v[108:111], v[150:153], v[226:229], v[108:111]
	v_mfma_f32_16x16x32_bf16 v[104:107], v[194:197], v[226:229], v[104:107]
	v_mfma_f32_16x16x32_bf16 v[92:95], v[150:153], v[234:237], v[92:95]
	v_mfma_f32_16x16x32_bf16 v[88:91], v[194:197], v[234:237], v[88:91]
	v_mfma_f32_16x16x32_bf16 v[76:79], v[150:153], v[242:245], v[76:79]
	v_mfma_f32_16x16x32_bf16 v[72:75], v[194:197], v[242:245], v[72:75]
	v_mfma_f32_16x16x32_bf16 v[124:127], v[190:193], v[222:225], v[124:127]
	v_mfma_f32_16x16x32_bf16 v[120:123], v[198:201], v[222:225], v[120:123]
	v_mfma_f32_16x16x32_bf16 v[108:111], v[190:193], v[230:233], v[108:111]
	v_mfma_f32_16x16x32_bf16 v[104:107], v[198:201], v[230:233], v[104:107]
	v_mfma_f32_16x16x32_bf16 v[92:95], v[190:193], v[238:241], v[92:95]
	v_mfma_f32_16x16x32_bf16 v[88:91], v[198:201], v[238:241], v[88:91]
	v_mfma_f32_16x16x32_bf16 v[76:79], v[190:193], v[246:249], v[76:79]
	v_mfma_f32_16x16x32_bf16 v[72:75], v[198:201], v[246:249], v[72:75]
	s_setprio 0
	s_setprio 1
	s_setprio 0
	s_barrier
	s_add_i32 s40, s40, s34
	v_lshl_add_u64 v[154:155], s[22:23], 0, v[142:143]
	s_mov_b32 m0, s40
	ds_read_b128 v[218:221], v178 offset:16384
	ds_read_b128 v[222:225], v178 offset:17408
	ds_read_b128 v[226:229], v178 offset:18432
	ds_read_b128 v[230:233], v178 offset:19456
	ds_read_b128 v[234:237], v178 offset:20480
	ds_read_b128 v[238:241], v178 offset:21504
	ds_read_b128 v[242:245], v178 offset:22528
	ds_read_b128 v[246:249], v178 offset:23552
	global_load_lds_dwordx4 v[154:155], off
	s_add_i32 m0, s40, 0x2000
	s_add_u32 s40, s22, 0x40000
	v_lshl_add_u64 v[180:181], s[22:23], 0, v[138:139]
	s_addc_u32 s41, s23, 0
	s_add_i32 s44, s44, s34
	global_load_lds_dwordx4 v[180:181], off
	v_lshl_add_u64 v[250:251], s[40:41], 0, v[142:143]
	s_mov_b32 m0, s44
	v_lshl_add_u64 v[134:135], s[24:25], 0, v[140:141]
	v_lshl_add_u64 v[250:251], s[40:41], 0, v[138:139]
	s_add_i32 m0, s44, 0x2000
	s_nop 0
	v_lshl_add_u64 v[250:251], s[24:25], 0, v[144:145]
	s_mov_b32 m0, s35
	s_nop 0
	global_load_lds_dwordx4 v[250:251], off
	s_mov_b32 m0, s42
	s_nop 0
	global_load_lds_dwordx4 v[134:135], off
	s_waitcnt vmcnt(6)
	s_waitcnt lgkmcnt(0)
	s_barrier
	s_setprio 1
	s_waitcnt lgkmcnt(0)
	v_mfma_f32_16x16x32_bf16 v[60:63], v[150:153], v[218:221], v[60:63]
	v_mfma_f32_16x16x32_bf16 v[56:59], v[194:197], v[218:221], v[56:59]
	v_mfma_f32_16x16x32_bf16 v[44:47], v[150:153], v[226:229], v[44:47]
	v_mfma_f32_16x16x32_bf16 v[40:43], v[194:197], v[226:229], v[40:43]
	v_mfma_f32_16x16x32_bf16 v[28:31], v[150:153], v[234:237], v[28:31]
	v_mfma_f32_16x16x32_bf16 v[24:27], v[194:197], v[234:237], v[24:27]
	v_mfma_f32_16x16x32_bf16 v[12:15], v[150:153], v[242:245], v[12:15]
	v_mfma_f32_16x16x32_bf16 v[8:11], v[194:197], v[242:245], v[8:11]
	v_mfma_f32_16x16x32_bf16 v[60:63], v[190:193], v[222:225], v[60:63]
	v_mfma_f32_16x16x32_bf16 v[56:59], v[198:201], v[222:225], v[56:59]
	v_mfma_f32_16x16x32_bf16 v[44:47], v[190:193], v[230:233], v[44:47]
	v_mfma_f32_16x16x32_bf16 v[40:43], v[198:201], v[230:233], v[40:43]
	v_mfma_f32_16x16x32_bf16 v[28:31], v[190:193], v[238:241], v[28:31]
	v_mfma_f32_16x16x32_bf16 v[24:27], v[198:201], v[238:241], v[24:27]
	v_mfma_f32_16x16x32_bf16 v[12:15], v[190:193], v[246:249], v[12:15]
	v_mfma_f32_16x16x32_bf16 v[8:11], v[198:201], v[246:249], v[8:11]
	s_setprio 0
	s_setprio 1
	s_setprio 0
	s_barrier
	s_add_i32 s40, 0, 0x18000
	v_add_u32_e32 v128, s40, v157
	s_add_i32 s41, 0, 0x1c000
	ds_read_b128 v[150:153], v128
	ds_read_b128 v[190:193], v128 offset:1024
	ds_read_b128 v[194:197], v128 offset:2048
	ds_read_b128 v[198:201], v128 offset:3072
	v_add_u32_e32 v128, s41, v157
	s_add_u32 s24, s24, 0x40000
	s_addc_u32 s25, s25, 0
	s_mov_b32 m0, s43
	v_lshl_add_u64 v[136:137], s[24:25], 0, v[144:145]
	ds_read_b128 v[218:221], v178 offset:32768
	ds_read_b128 v[222:225], v178 offset:33792
	ds_read_b128 v[226:229], v178 offset:34816
	ds_read_b128 v[230:233], v178 offset:35840
	ds_read_b128 v[234:237], v178 offset:36864
	ds_read_b128 v[238:241], v178 offset:37888
	ds_read_b128 v[242:245], v178 offset:38912
	ds_read_b128 v[246:249], v178 offset:39936
	global_load_lds_dwordx4 v[136:137], off
	v_lshl_add_u64 v[136:137], s[24:25], 0, v[140:141]
	s_mov_b32 m0, s51
	s_nop 0
	global_load_lds_dwordx4 v[136:137], off
	s_waitcnt vmcnt(6)
	s_waitcnt lgkmcnt(0)
	s_barrier
	s_setprio 1
	s_waitcnt lgkmcnt(0)
	v_mfma_f32_16x16x32_bf16 v[124:127], v[150:153], v[218:221], v[124:127]
	v_mfma_f32_16x16x32_bf16 v[120:123], v[194:197], v[218:221], v[120:123]
	v_mfma_f32_16x16x32_bf16 v[108:111], v[150:153], v[226:229], v[108:111]
	v_mfma_f32_16x16x32_bf16 v[104:107], v[194:197], v[226:229], v[104:107]
	v_mfma_f32_16x16x32_bf16 v[92:95], v[150:153], v[234:237], v[92:95]
	v_mfma_f32_16x16x32_bf16 v[88:91], v[194:197], v[234:237], v[88:91]
	v_mfma_f32_16x16x32_bf16 v[76:79], v[150:153], v[242:245], v[76:79]
	v_mfma_f32_16x16x32_bf16 v[72:75], v[194:197], v[242:245], v[72:75]
	v_mfma_f32_16x16x32_bf16 v[124:127], v[190:193], v[222:225], v[124:127]
	v_mfma_f32_16x16x32_bf16 v[120:123], v[198:201], v[222:225], v[120:123]
	v_mfma_f32_16x16x32_bf16 v[108:111], v[190:193], v[230:233], v[108:111]
	v_mfma_f32_16x16x32_bf16 v[104:107], v[198:201], v[230:233], v[104:107]
	v_mfma_f32_16x16x32_bf16 v[92:95], v[190:193], v[238:241], v[92:95]
	v_mfma_f32_16x16x32_bf16 v[88:91], v[198:201], v[238:241], v[88:91]
	v_mfma_f32_16x16x32_bf16 v[76:79], v[190:193], v[246:249], v[76:79]
	v_mfma_f32_16x16x32_bf16 v[72:75], v[198:201], v[246:249], v[72:75]
	s_setprio 0
	s_setprio 1
	s_setprio 0
	s_barrier
	s_add_i32 s24, s40, s34
	v_lshl_add_u64 v[136:137], v[154:155], 0, s[2:3]
	s_mov_b32 m0, s24
	ds_read_b128 v[218:221], v178 offset:49152
	ds_read_b128 v[222:225], v178 offset:50176
	ds_read_b128 v[226:229], v178 offset:51200
	ds_read_b128 v[230:233], v178 offset:52224
	ds_read_b128 v[234:237], v178 offset:53248
	ds_read_b128 v[238:241], v178 offset:54272
	ds_read_b128 v[242:245], v178 offset:55296
	ds_read_b128 v[246:249], v178 offset:56320
	global_load_lds_dwordx4 v[136:137], off
	s_add_i32 m0, s24, 0x2000
	s_add_u32 s22, s22, 0x40080
	v_lshl_add_u64 v[136:137], v[180:181], 0, s[2:3]
	s_addc_u32 s23, s23, 0
	s_add_i32 s24, s41, s34
	global_load_lds_dwordx4 v[136:137], off
	v_lshl_add_u64 v[136:137], s[22:23], 0, v[142:143]
	s_mov_b32 m0, s24
	v_lshl_add_u64 v[134:135], v[134:135], 0, s[2:3]
	v_lshl_add_u64 v[136:137], s[22:23], 0, v[138:139]
	s_add_i32 m0, s24, 0x2000
	s_nop 0
	v_lshl_add_u64 v[136:137], v[250:251], 0, s[2:3]
	s_mov_b32 m0, s78
	s_nop 0
	global_load_lds_dwordx4 v[136:137], off
	s_mov_b32 m0, s79
	s_nop 0
	global_load_lds_dwordx4 v[134:135], off
	s_waitcnt vmcnt(6)
	s_waitcnt lgkmcnt(0)
	s_barrier
	s_setprio 1
	s_waitcnt lgkmcnt(0)
	v_mfma_f32_16x16x32_bf16 v[60:63], v[150:153], v[218:221], v[60:63]
	v_mfma_f32_16x16x32_bf16 v[56:59], v[194:197], v[218:221], v[56:59]
	v_mfma_f32_16x16x32_bf16 v[44:47], v[150:153], v[226:229], v[44:47]
	v_mfma_f32_16x16x32_bf16 v[40:43], v[194:197], v[226:229], v[40:43]
	v_mfma_f32_16x16x32_bf16 v[28:31], v[150:153], v[234:237], v[28:31]
	v_mfma_f32_16x16x32_bf16 v[24:27], v[194:197], v[234:237], v[24:27]
	v_mfma_f32_16x16x32_bf16 v[12:15], v[150:153], v[242:245], v[12:15]
	v_mfma_f32_16x16x32_bf16 v[8:11], v[194:197], v[242:245], v[8:11]
	v_mfma_f32_16x16x32_bf16 v[60:63], v[190:193], v[222:225], v[60:63]
	v_mfma_f32_16x16x32_bf16 v[56:59], v[198:201], v[222:225], v[56:59]
	v_mfma_f32_16x16x32_bf16 v[44:47], v[190:193], v[230:233], v[44:47]
	v_mfma_f32_16x16x32_bf16 v[40:43], v[198:201], v[230:233], v[40:43]
	v_mfma_f32_16x16x32_bf16 v[28:31], v[190:193], v[238:241], v[28:31]
	v_mfma_f32_16x16x32_bf16 v[24:27], v[198:201], v[238:241], v[24:27]
	v_mfma_f32_16x16x32_bf16 v[12:15], v[190:193], v[246:249], v[12:15]
	v_mfma_f32_16x16x32_bf16 v[8:11], v[198:201], v[246:249], v[8:11]
	s_setprio 0
	s_setprio 1
	s_setprio 0
	s_barrier
	s_add_i32 s39, s39, 2
	s_add_u32 s0, s0, 0x100
	s_addc_u32 s1, s1, 0
	s_add_u32 s33, s33, 0x100
	s_addc_u32 s38, s38, 0
	s_cmp_gt_u32 s39, 13
	s_cbranch_scc0 .Lh0_W_509
	s_and_b64 vcc, exec, s[6:7]
	s_cbranch_vccz .Lh0_W_512
	s_barrier

.Lh0_W_522:
	s_or_b64 exec, exec, s[22:23]
	v_or_b32_e32 v124, 0x80, v150
	s_movk_i32 s22, 0xe80
	v_cmp_gt_i32_e64 s[40:41], s22, v124
	s_mov_b64 s[40:41], 0
	s_and_saveexec_b64 s[22:23], s[40:41]
	s_cbranch_execz .Lh0_W_532
	v_cvt_pk_bf16_f32 v120, v116, v117
	v_cvt_pk_bf16_f32 v121, v118, v119
	v_cvt_pk_bf16_f32 v122, v112, v113
	v_cvt_pk_bf16_f32 v123, v114, v115
	v_lshl_add_u64 v[126:127], v[150:151], 1, v[152:153]
	global_store_dwordx4 v[126:127], v[120:123], off offset:256
	s_and_b64 exec, exec, s[0:1]
	s_cbranch_execz .Lh0_W_532
	s_add_i32 s0, s15, 0xfffffb00
	s_cmpk_lt_u32 s0, 0x200
	s_cbranch_scc1 .Lh0_W_529
	s_movk_i32 s0, 0xd7f
	v_cmp_lt_i32_e32 vcc, s0, v124
	s_mov_b64 s[24:25], 0
	s_mov_b64 s[0:1], 0
	s_and_saveexec_b64 s[26:27], vcc
	s_cbranch_execz .Lh0_W_527
	v_readlane_b32 s0, v254, 34
	s_add_i32 s0, s33, s0
	s_lshl_b32 s29, s0, 1
	v_readlane_b32 s1, v254, 35
	s_cmpk_gt_u32 s15, 0xdff
	s_cselect_b64 s[0:1], -1, 0
	v_cndmask_b32_e64 v120, 0, 1, s[0:1]
	v_or_b32_e32 v120, s29, v120
	v_ashrrev_i32_e32 v121, 31, v120
	s_and_b64 s[0:1], s[0:1], exec
	v_lshlrev_b64 v[120:121], 17, v[120:121]
	s_movk_i32 s0, 0xf200
	v_lshl_add_u64 v[120:121], s[10:11], 0, v[120:121]
	v_lshlrev_b32_e32 v128, 2, v180
	s_cselect_b32 s28, s0, 0xfffff280
	v_lshl_add_u64 v[120:121], v[120:121], 0, v[128:129]
	s_mov_b64 s[0:1], exec

.Lh1_W_509:
	s_add_u32 s22, s0, 0xfffc0080
	s_addc_u32 s23, s1, -1
	s_add_i32 s40, 0, 0x10000
	s_cmp_eq_u32 s39, 12
	s_cselect_b32 s25, s17, s23
	s_cselect_b32 s24, s28, s22
	v_add_u32_e32 v128, s40, v157
	s_cselect_b32 s23, s15, s38
	s_cselect_b32 s22, s29, s33
	s_add_i32 s44, 0, 0x14000
	v_add_u32_e32 v128, s44, v157
	ds_read_b128 v[202:205], v128
	ds_read_b128 v[206:209], v128 offset:1024
	ds_read_b128 v[210:213], v128 offset:2048
	ds_read_b128 v[214:217], v128 offset:3072
	v_lshl_add_u64 v[154:155], s[0:1], 0, v[146:147]
	s_add_i32 m0, s35, 0xc000
	ds_read_b128 v[218:221], v178
	ds_read_b128 v[222:225], v178 offset:1024
	ds_read_b128 v[226:229], v178 offset:2048
	ds_read_b128 v[230:233], v178 offset:3072
	ds_read_b128 v[234:237], v178 offset:4096
	ds_read_b128 v[238:241], v178 offset:5120
	ds_read_b128 v[242:245], v178 offset:6144
	ds_read_b128 v[246:249], v178 offset:7168
	global_load_lds_dwordx4 v[154:155], off
	v_lshl_add_u64 v[154:155], s[0:1], 0, v[148:149]
	s_add_i32 m0, s35, 0xe000
	s_nop 0
	global_load_lds_dwordx4 v[154:155], off
	s_waitcnt vmcnt(6)
	s_waitcnt lgkmcnt(0)
	s_barrier
	s_setprio 1
	s_waitcnt lgkmcnt(0)
	s_setprio 0
	s_setprio 1
	v_mfma_f32_16x16x32_bf16 v[116:119], v[202:205], v[218:221], v[116:119]
	v_mfma_f32_16x16x32_bf16 v[112:115], v[210:213], v[218:221], v[112:115]
	v_mfma_f32_16x16x32_bf16 v[100:103], v[202:205], v[226:229], v[100:103]
	v_mfma_f32_16x16x32_bf16 v[96:99], v[210:213], v[226:229], v[96:99]
	v_mfma_f32_16x16x32_bf16 v[84:87], v[202:205], v[234:237], v[84:87]
	v_mfma_f32_16x16x32_bf16 v[80:83], v[210:213], v[234:237], v[80:83]
	v_mfma_f32_16x16x32_bf16 v[68:71], v[202:205], v[242:245], v[68:71]
	v_mfma_f32_16x16x32_bf16 v[64:67], v[210:213], v[242:245], v[64:67]
	v_mfma_f32_16x16x32_bf16 v[116:119], v[206:209], v[222:225], v[116:119]
	v_mfma_f32_16x16x32_bf16 v[112:115], v[214:217], v[222:225], v[112:115]
	v_mfma_f32_16x16x32_bf16 v[100:103], v[206:209], v[230:233], v[100:103]
	v_mfma_f32_16x16x32_bf16 v[96:99], v[214:217], v[230:233], v[96:99]
	v_mfma_f32_16x16x32_bf16 v[84:87], v[206:209], v[238:241], v[84:87]
	v_mfma_f32_16x16x32_bf16 v[80:83], v[214:217], v[238:241], v[80:83]
	v_mfma_f32_16x16x32_bf16 v[68:71], v[206:209], v[246:249], v[68:71]
	v_mfma_f32_16x16x32_bf16 v[64:67], v[214:217], v[246:249], v[64:67]
	s_setprio 0
	s_barrier
	s_add_i32 s40, s40, s34
	v_lshl_add_u64 v[154:155], s[22:23], 0, v[142:143]
	s_mov_b32 m0, s40
	ds_read_b128 v[218:221], v178 offset:16384
	ds_read_b128 v[222:225], v178 offset:17408
	ds_read_b128 v[226:229], v178 offset:18432
	ds_read_b128 v[230:233], v178 offset:19456
	ds_read_b128 v[234:237], v178 offset:20480
	ds_read_b128 v[238:241], v178 offset:21504
	ds_read_b128 v[242:245], v178 offset:22528
	ds_read_b128 v[246:249], v178 offset:23552
	s_add_i32 m0, s40, 0x2000
	s_add_u32 s40, s22, 0x40000
	v_lshl_add_u64 v[180:181], s[22:23], 0, v[138:139]
	s_addc_u32 s41, s23, 0
	s_add_i32 s44, s44, s34
	v_lshl_add_u64 v[250:251], s[40:41], 0, v[142:143]
	s_mov_b32 m0, s44
	v_lshl_add_u64 v[134:135], s[24:25], 0, v[140:141]
	global_load_lds_dwordx4 v[250:251], off
	v_lshl_add_u64 v[250:251], s[40:41], 0, v[138:139]
	s_add_i32 m0, s44, 0x2000
	s_nop 0
	global_load_lds_dwordx4 v[250:251], off
	v_lshl_add_u64 v[250:251], s[24:25], 0, v[144:145]
	s_mov_b32 m0, s35
	s_nop 0
	global_load_lds_dwordx4 v[250:251], off
	s_mov_b32 m0, s42
	s_nop 0
	global_load_lds_dwordx4 v[134:135], off
	s_waitcnt vmcnt(6)
	s_waitcnt lgkmcnt(0)
	s_barrier
	s_setprio 1
	s_waitcnt lgkmcnt(0)
	s_setprio 0
	s_setprio 1
	v_mfma_f32_16x16x32_bf16 v[52:55], v[202:205], v[218:221], v[52:55]
	v_mfma_f32_16x16x32_bf16 v[48:51], v[210:213], v[218:221], v[48:51]
	v_mfma_f32_16x16x32_bf16 v[36:39], v[202:205], v[226:229], v[36:39]
	v_mfma_f32_16x16x32_bf16 v[32:35], v[210:213], v[226:229], v[32:35]
	v_mfma_f32_16x16x32_bf16 v[20:23], v[202:205], v[234:237], v[20:23]
	v_mfma_f32_16x16x32_bf16 v[16:19], v[210:213], v[234:237], v[16:19]
	v_mfma_f32_16x16x32_bf16 v[4:7], v[202:205], v[242:245], v[4:7]
	v_mfma_f32_16x16x32_bf16 v[0:3], v[210:213], v[242:245], v[0:3]
	v_mfma_f32_16x16x32_bf16 v[52:55], v[206:209], v[222:225], v[52:55]
	v_mfma_f32_16x16x32_bf16 v[48:51], v[214:217], v[222:225], v[48:51]
	v_mfma_f32_16x16x32_bf16 v[36:39], v[206:209], v[230:233], v[36:39]
	v_mfma_f32_16x16x32_bf16 v[32:35], v[214:217], v[230:233], v[32:35]
	v_mfma_f32_16x16x32_bf16 v[20:23], v[206:209], v[238:241], v[20:23]
	v_mfma_f32_16x16x32_bf16 v[16:19], v[214:217], v[238:241], v[16:19]
	v_mfma_f32_16x16x32_bf16 v[4:7], v[206:209], v[246:249], v[4:7]
	v_mfma_f32_16x16x32_bf16 v[0:3], v[214:217], v[246:249], v[0:3]
	s_setprio 0
	s_barrier
	s_add_i32 s40, 0, 0x18000
	v_add_u32_e32 v128, s40, v157
	s_add_i32 s41, 0, 0x1c000
	v_add_u32_e32 v128, s41, v157
	ds_read_b128 v[202:205], v128
	ds_read_b128 v[206:209], v128 offset:1024
	ds_read_b128 v[210:213], v128 offset:2048
	ds_read_b128 v[214:217], v128 offset:3072
	s_add_u32 s24, s24, 0x40000
	s_addc_u32 s25, s25, 0
	s_mov_b32 m0, s43
	v_lshl_add_u64 v[136:137], s[24:25], 0, v[144:145]
	ds_read_b128 v[218:221], v178 offset:32768
	ds_read_b128 v[222:225], v178 offset:33792
	ds_read_b128 v[226:229], v178 offset:34816
	ds_read_b128 v[230:233], v178 offset:35840
	ds_read_b128 v[234:237], v178 offset:36864
	ds_read_b128 v[238:241], v178 offset:37888
	ds_read_b128 v[242:245], v178 offset:38912
	ds_read_b128 v[246:249], v178 offset:39936
	global_load_lds_dwordx4 v[136:137], off
	v_lshl_add_u64 v[136:137], s[24:25], 0, v[140:141]
	s_mov_b32 m0, s51
	s_nop 0
	global_load_lds_dwordx4 v[136:137], off
	s_waitcnt vmcnt(6)
	s_waitcnt lgkmcnt(0)
	s_barrier
	s_setprio 1
	s_waitcnt lgkmcnt(0)
	s_setprio 0
	s_setprio 1
	v_mfma_f32_16x16x32_bf16 v[116:119], v[202:205], v[218:221], v[116:119]
	v_mfma_f32_16x16x32_bf16 v[112:115], v[210:213], v[218:221], v[112:115]
	v_mfma_f32_16x16x32_bf16 v[100:103], v[202:205], v[226:229], v[100:103]
	v_mfma_f32_16x16x32_bf16 v[96:99], v[210:213], v[226:229], v[96:99]
	v_mfma_f32_16x16x32_bf16 v[84:87], v[202:205], v[234:237], v[84:87]
	v_mfma_f32_16x16x32_bf16 v[80:83], v[210:213], v[234:237], v[80:83]
	v_mfma_f32_16x16x32_bf16 v[68:71], v[202:205], v[242:245], v[68:71]
	v_mfma_f32_16x16x32_bf16 v[64:67], v[210:213], v[242:245], v[64:67]
	v_mfma_f32_16x16x32_bf16 v[116:119], v[206:209], v[222:225], v[116:119]
	v_mfma_f32_16x16x32_bf16 v[112:115], v[214:217], v[222:225], v[112:115]
	v_mfma_f32_16x16x32_bf16 v[100:103], v[206:209], v[230:233], v[100:103]
	v_mfma_f32_16x16x32_bf16 v[96:99], v[214:217], v[230:233], v[96:99]
	v_mfma_f32_16x16x32_bf16 v[84:87], v[206:209], v[238:241], v[84:87]
	v_mfma_f32_16x16x32_bf16 v[80:83], v[214:217], v[238:241], v[80:83]
	v_mfma_f32_16x16x32_bf16 v[68:71], v[206:209], v[246:249], v[68:71]
	v_mfma_f32_16x16x32_bf16 v[64:67], v[214:217], v[246:249], v[64:67]
	s_setprio 0
	s_barrier
	s_add_i32 s24, s40, s34
	v_lshl_add_u64 v[136:137], v[154:155], 0, s[2:3]
	s_mov_b32 m0, s24
	ds_read_b128 v[218:221], v178 offset:49152
	ds_read_b128 v[222:225], v178 offset:50176
	ds_read_b128 v[226:229], v178 offset:51200
	ds_read_b128 v[230:233], v178 offset:52224
	ds_read_b128 v[234:237], v178 offset:53248
	ds_read_b128 v[238:241], v178 offset:54272
	ds_read_b128 v[242:245], v178 offset:55296
	ds_read_b128 v[246:249], v178 offset:56320
	s_add_i32 m0, s24, 0x2000
	s_add_u32 s22, s22, 0x40080
	v_lshl_add_u64 v[136:137], v[180:181], 0, s[2:3]
	s_addc_u32 s23, s23, 0
	s_add_i32 s24, s41, s34
	v_lshl_add_u64 v[136:137], s[22:23], 0, v[142:143]
	s_mov_b32 m0, s24
	v_lshl_add_u64 v[134:135], v[134:135], 0, s[2:3]
	global_load_lds_dwordx4 v[136:137], off
	v_lshl_add_u64 v[136:137], s[22:23], 0, v[138:139]
	s_add_i32 m0, s24, 0x2000
	s_nop 0
	global_load_lds_dwordx4 v[136:137], off
	v_lshl_add_u64 v[136:137], v[250:251], 0, s[2:3]
	s_mov_b32 m0, s78
	s_nop 0
	global_load_lds_dwordx4 v[136:137], off
	s_mov_b32 m0, s79
	s_nop 0
	global_load_lds_dwordx4 v[134:135], off
	s_waitcnt vmcnt(6)
	s_waitcnt lgkmcnt(0)
	s_barrier
	s_setprio 1
	s_waitcnt lgkmcnt(0)
	s_setprio 0
	s_setprio 1
	v_mfma_f32_16x16x32_bf16 v[52:55], v[202:205], v[218:221], v[52:55]
	v_mfma_f32_16x16x32_bf16 v[48:51], v[210:213], v[218:221], v[48:51]
	v_mfma_f32_16x16x32_bf16 v[36:39], v[202:205], v[226:229], v[36:39]
	v_mfma_f32_16x16x32_bf16 v[32:35], v[210:213], v[226:229], v[32:35]
	v_mfma_f32_16x16x32_bf16 v[20:23], v[202:205], v[234:237], v[20:23]
	v_mfma_f32_16x16x32_bf16 v[16:19], v[210:213], v[234:237], v[16:19]
	v_mfma_f32_16x16x32_bf16 v[4:7], v[202:205], v[242:245], v[4:7]
	v_mfma_f32_16x16x32_bf16 v[0:3], v[210:213], v[242:245], v[0:3]
	v_mfma_f32_16x16x32_bf16 v[52:55], v[206:209], v[222:225], v[52:55]
	v_mfma_f32_16x16x32_bf16 v[48:51], v[214:217], v[222:225], v[48:51]
	v_mfma_f32_16x16x32_bf16 v[36:39], v[206:209], v[230:233], v[36:39]
	v_mfma_f32_16x16x32_bf16 v[32:35], v[214:217], v[230:233], v[32:35]
	v_mfma_f32_16x16x32_bf16 v[20:23], v[206:209], v[238:241], v[20:23]
	v_mfma_f32_16x16x32_bf16 v[16:19], v[214:217], v[238:241], v[16:19]
	v_mfma_f32_16x16x32_bf16 v[4:7], v[206:209], v[246:249], v[4:7]
	v_mfma_f32_16x16x32_bf16 v[0:3], v[214:217], v[246:249], v[0:3]
	s_setprio 0
	s_barrier
	s_add_i32 s39, s39, 2
	s_add_u32 s0, s0, 0x100
	s_addc_u32 s1, s1, 0
	s_add_u32 s33, s33, 0x100
	s_addc_u32 s38, s38, 0
	s_cmp_gt_u32 s39, 13
	s_cbranch_scc0 .Lh1_W_509
	s_and_b64 vcc, exec, s[6:7]
	s_cbranch_vccz .Lh1_W_512
	s_barrier
.Lh1_W_512:
	s_lshl_b32 s17, s27, 8
	s_add_i32 s17, s17, s77
	v_or_b32_e32 v128, s17, v156
	v_mad_i64_i32 v[134:135], s[0:1], v128, s87, 0
	s_ashr_i32 s15, s17, 6
	s_movk_i32 s0, 0x2000
	s_and_b32 s33, s15, -4
	s_lshl_b32 s15, s26, 8
	v_cmp_gt_i32_e64 s[0:1], s0, v128
	v_lshlrev_b32_e32 v136, 7, v128
	v_lshlrev_b32_e32 v128, 8, v128
	v_or_b32_e32 v150, s15, v158
	s_movk_i32 s22, 0xe80
	v_and_b32_e32 v180, 0x6780, v136
	v_and_b32_e32 v179, 0xcf00, v128
	v_cmp_gt_i32_e64 s[38:39], s22, v150
	s_mov_b64 s[38:39], 0
	v_lshl_add_u64 v[152:153], s[8:9], 0, v[134:135]
	v_ashrrev_i32_e32 v151, 31, v150
	s_and_saveexec_b64 s[22:23], s[38:39]
	s_cbranch_execz .Lh1_W_522
	v_cvt_pk_bf16_f32 v190, v124, v125
	v_cvt_pk_bf16_f32 v191, v126, v127
	v_cvt_pk_bf16_f32 v192, v120, v121
	v_cvt_pk_bf16_f32 v193, v122, v123
	v_lshl_add_u64 v[134:135], v[150:151], 1, v[152:153]
	global_store_dwordx4 v[134:135], v[190:193], off
	s_and_b64 exec, exec, s[0:1]
	s_cbranch_execz .Lh1_W_522
	s_add_i32 s24, s15, 0xfffffa80
	s_cmpk_gt_u32 s24, 0x1ff
	s_cbranch_scc0 .Lh1_W_519
	s_movk_i32 s24, 0xd7f
	v_cmp_lt_i32_e32 vcc, s24, v150
	s_mov_b64 s[26:27], 0
	s_mov_b64 s[24:25], 0
	s_and_saveexec_b64 s[28:29], vcc
	s_xor_b64 s[28:29], exec, s[28:29]
	s_cbranch_execz .Lh1_W_517
	v_readlane_b32 s24, v254, 34
	s_add_i32 s24, s33, s24
	s_lshl_b32 s41, s24, 1
	v_readlane_b32 s25, v254, 35
	s_cmpk_gt_u32 s15, 0xdff
	s_cselect_b64 s[24:25], -1, 0
	v_cndmask_b32_e64 v128, 0, 1, s[24:25]
	v_or_b32_e32 v134, s41, v128
	v_ashrrev_i32_e32 v135, 31, v134
	s_and_b64 s[24:25], s[24:25], exec
	v_lshlrev_b64 v[134:135], 17, v[134:135]
	s_movk_i32 s24, 0xf200
	v_lshl_add_u64 v[134:135], s[10:11], 0, v[134:135]
	v_lshlrev_b32_e32 v128, 2, v180
	s_cselect_b32 s40, s24, 0xfffff280
	v_lshl_add_u64 v[154:155], v[134:135], 0, v[128:129]
	s_mov_b64 s[24:25], exec
